# P5/P8 residual epilogue: growing load ring - consumed accumulator quads become load buffers, 9 -> ~24 residual loads in flight
# speedup vs baseline: 1.0114x; 1.0027x over previous
;     __device__ __forceinline__ void operator()(const f32x4 (&acc)[2][2][4][2], const Unit& u, int wr, int wc, int fr, int fq) const {
;     ...
;         const bool isctx = u.pm >= 128;
;         const float* inb = isctx ? in_ctx : in_lat; float* outb = isctx ? out_ctx : out_lat;
;         const int pml = isctx ? u.pm - 128 : u.pm;
;         const float* gp = gate + (size_t)(isctx ? 16 : (u.pm >> 3)) * 6144;
;         const int row0 = pml * BM + wr * 64 + fr, col0 = u.pn * BM + wc * 32 + 4 * fq;
;         f32x4 gv[2][2];
; #pragma unroll
;         for (int bj = 0; bj < 2; ++bj)
; #pragma unroll
;             for (int n = 0; n < 2; ++n) gv[bj][n] = *(const f32x4*)(gp + col0 + bj * HALF + n * 16);
; #pragma unroll
;         for (int ai = 0; ai < 2; ++ai)
; #pragma unroll
;             for (int m = 0; m < 4; ++m) { const size_t ro = (size_t)(row0 + ai * HALF + m * 16) * 1024 + col0;
; #pragma unroll
;                 for (int bj = 0; bj < 2; ++bj)
; #pragma unroll
;                     for (int n = 0; n < 2; ++n) { const f32x4 x = *(const f32x4*)(inb + ro + bj * HALF + n * 16);
;                         *(f32x4*)(outb + ro + bj * HALF + n * 16) = x + gv[bj][n] * acc[ai][bj][m][n]; } }
.LBB0_979:
	s_and_b64 s[2:3], exec, s[26:27]
	v_readlane_b32 s2, v255, 39
	v_readlane_b32 s16, v255, 41
	v_readlane_b32 s3, v255, 40
	v_readlane_b32 s17, v255, 42
	s_cselect_b32 s3, s3, s17
	s_cselect_b32 s2, s2, s16
	s_cselect_b32 s17, s65, s43
	s_cselect_b32 s16, s64, s42
	s_lshl_b64 s[18:19], s[28:29], 2
	s_add_u32 s18, s52, s18
	s_addc_u32 s19, s53, s19
	s_lshl_b32 s5, s20, 8
	s_add_i32 s21, s5, 0xffff8000
	s_and_b64 s[26:27], exec, s[26:27]
	s_cselect_b32 s5, s21, s5
	v_add_u32_e32 v174, s5, v160
	v_lshl_or_b32 v172, s11, 8, v161
	v_ashrrev_i32_e32 v175, 31, v174
	v_ashrrev_i32_e32 v173, 31, v172
	v_lshlrev_b64 v[146:147], 10, v[174:175]
	v_lshl_add_u64 v[146:147], v[146:147], 0, v[172:173]
	v_lshlrev_b64 v[170:171], 2, v[146:147]
	v_lshl_add_u64 v[130:131], v[172:173], 2, s[18:19]
	v_lshl_add_u64 v[150:151], s[2:3], 0, v[170:171]
	global_load_dwordx4 v[142:145], v[130:131], off
	global_load_dwordx4 v[138:141], v[130:131], off offset:64
	global_load_dwordx4 v[134:137], v[130:131], off offset:512
	s_nop 0
	global_load_dwordx4 v[130:133], v[130:131], off offset:576
	v_lshl_add_u64 v[152:153], s[16:17], 0, v[170:171]
	s_mov_b64 s[98:99], 0x10000
	v_lshl_add_u64 v[176:177], v[150:151], 0, s[98:99]
	v_lshl_add_u64 v[178:179], v[152:153], 0, s[98:99]
	s_mov_b64 s[98:99], 0x20000
	v_lshl_add_u64 v[180:181], v[150:151], 0, s[98:99]
	v_lshl_add_u64 v[182:183], v[152:153], 0, s[98:99]
	s_mov_b64 s[98:99], 0x30000
	v_lshl_add_u64 v[184:185], v[150:151], 0, s[98:99]
	v_lshl_add_u64 v[186:187], v[152:153], 0, s[98:99]
	s_mov_b64 s[98:99], 0x80000
	v_lshl_add_u64 v[188:189], v[150:151], 0, s[98:99]
	v_lshl_add_u64 v[190:191], v[152:153], 0, s[98:99]
	s_mov_b64 s[98:99], 0x90000
	v_lshl_add_u64 v[192:193], v[150:151], 0, s[98:99]
	v_lshl_add_u64 v[194:195], v[152:153], 0, s[98:99]
	s_mov_b64 s[98:99], 0xa0000
	v_lshl_add_u64 v[196:197], v[150:151], 0, s[98:99]
	v_lshl_add_u64 v[198:199], v[152:153], 0, s[98:99]
	s_mov_b64 s[98:99], 0xb0000
	v_lshl_add_u64 v[200:201], v[150:151], 0, s[98:99]
	v_lshl_add_u64 v[202:203], v[152:153], 0, s[98:99]
	global_load_dwordx4 v[204:207], v[150:151], off
	global_load_dwordx4 v[212:215], v[150:151], off offset:64
	global_load_dwordx4 v[224:227], v[150:151], off offset:512
	global_load_dwordx4 v[228:231], v[150:151], off offset:576
	global_load_dwordx4 v[232:235], v[176:177], off
	global_load_dwordx4 v[236:239], v[176:177], off offset:64
	global_load_dwordx4 v[240:243], v[176:177], off offset:512
	global_load_dwordx4 v[244:247], v[176:177], off offset:576
	global_load_dwordx4 v[248:251], v[180:181], off
	s_waitcnt vmcnt(8)
	v_pk_fma_f32 v[206:207], v[128:129], v[144:145], v[206:207]
	v_pk_fma_f32 v[204:205], v[126:127], v[142:143], v[204:205]
	global_store_dwordx4 v[152:153], v[204:207], off
	global_load_dwordx4 v[126:129], v[180:181], off offset:64
	s_waitcnt vmcnt(9)
	v_pk_fma_f32 v[214:215], v[124:125], v[140:141], v[214:215]
	v_pk_fma_f32 v[212:213], v[122:123], v[138:139], v[212:213]
	global_store_dwordx4 v[152:153], v[212:215], off offset:64
	global_load_dwordx4 v[204:207], v[180:181], off offset:512
	global_load_dwordx4 v[122:125], v[180:181], off offset:576
	s_waitcnt vmcnt(11)
	v_pk_fma_f32 v[226:227], v[112:113], v[136:137], v[226:227]
	v_pk_fma_f32 v[224:225], v[110:111], v[134:135], v[224:225]
	global_store_dwordx4 v[152:153], v[224:227], off offset:512
	global_load_dwordx4 v[212:215], v[184:185], off
	global_load_dwordx4 v[110:113], v[184:185], off offset:64
	s_waitcnt vmcnt(13)
	v_pk_fma_f32 v[230:231], v[104:105], v[132:133], v[230:231]
	v_pk_fma_f32 v[228:229], v[102:103], v[130:131], v[228:229]
	global_store_dwordx4 v[152:153], v[228:231], off offset:576
	global_load_dwordx4 v[224:227], v[184:185], off offset:512
	global_load_dwordx4 v[102:105], v[184:185], off offset:576
	s_waitcnt vmcnt(15)
	v_pk_fma_f32 v[234:235], v[120:121], v[144:145], v[234:235]
	v_pk_fma_f32 v[232:233], v[118:119], v[142:143], v[232:233]
	global_store_dwordx4 v[178:179], v[232:235], off
	global_load_dwordx4 v[228:231], v[188:189], off
	global_load_dwordx4 v[118:121], v[188:189], off offset:64
	s_waitcnt vmcnt(17)
	v_pk_fma_f32 v[238:239], v[116:117], v[140:141], v[238:239]
	v_pk_fma_f32 v[236:237], v[114:115], v[138:139], v[236:237]
	global_store_dwordx4 v[178:179], v[236:239], off offset:64
	global_load_dwordx4 v[232:235], v[188:189], off offset:512
	global_load_dwordx4 v[114:117], v[188:189], off offset:576
	s_waitcnt vmcnt(19)
	v_pk_fma_f32 v[242:243], v[96:97], v[136:137], v[242:243]
	v_pk_fma_f32 v[240:241], v[94:95], v[134:135], v[240:241]
	global_store_dwordx4 v[178:179], v[240:243], off offset:512
	global_load_dwordx4 v[236:239], v[192:193], off
	global_load_dwordx4 v[94:97], v[192:193], off offset:64
	s_waitcnt vmcnt(21)
	v_pk_fma_f32 v[246:247], v[88:89], v[132:133], v[246:247]
	v_pk_fma_f32 v[244:245], v[86:87], v[130:131], v[244:245]
	global_store_dwordx4 v[178:179], v[244:247], off offset:576
	global_load_dwordx4 v[240:243], v[192:193], off offset:512
	global_load_dwordx4 v[86:89], v[192:193], off offset:576
	s_waitcnt vmcnt(23)
;     __device__ __forceinline__ void operator()(const f32x4 (&acc)[2][2][4][2], const Unit& u, int wr, int wc, int fr, int fq) const {
;     ...
;         for (int ai = 0; ai < 2; ++ai)
; #pragma unroll
;             for (int m = 0; m < 4; ++m) { const size_t ro = (size_t)(row0 + ai * HALF + m * 16) * 1024 + col0;
; #pragma unroll
;                 for (int bj = 0; bj < 2; ++bj)
; #pragma unroll
;                     for (int n = 0; n < 2; ++n) { const f32x4 x = *(const f32x4*)(inb + ro + bj * HALF + n * 16);
;                         *(f32x4*)(outb + ro + bj * HALF + n * 16) = x + gv[bj][n] * acc[ai][bj][m][n]; } }
	v_pk_fma_f32 v[250:251], v[108:109], v[144:145], v[250:251]
	v_pk_fma_f32 v[248:249], v[106:107], v[142:143], v[248:249]
	global_store_dwordx4 v[182:183], v[248:251], off
	global_load_dwordx4 v[244:247], v[196:197], off
	global_load_dwordx4 v[106:109], v[196:197], off offset:64
	s_waitcnt vmcnt(24)
	v_pk_fma_f32 v[128:129], v[100:101], v[140:141], v[128:129]
	v_pk_fma_f32 v[126:127], v[98:99], v[138:139], v[126:127]
	global_store_dwordx4 v[182:183], v[126:129], off offset:64
	global_load_dwordx4 v[248:251], v[196:197], off offset:512
	global_load_dwordx4 v[98:101], v[196:197], off offset:576
	s_waitcnt vmcnt(25)
	v_pk_fma_f32 v[206:207], v[80:81], v[136:137], v[206:207]
	v_pk_fma_f32 v[204:205], v[78:79], v[134:135], v[204:205]
	global_store_dwordx4 v[182:183], v[204:207], off offset:512
	global_load_dwordx4 v[126:129], v[200:201], off
	global_load_dwordx4 v[78:81], v[200:201], off offset:64
	s_waitcnt vmcnt(27)
	v_pk_fma_f32 v[124:125], v[76:77], v[132:133], v[124:125]
	v_pk_fma_f32 v[122:123], v[74:75], v[130:131], v[122:123]
	global_store_dwordx4 v[182:183], v[122:125], off offset:576
	global_load_dwordx4 v[204:207], v[200:201], off offset:512
	global_load_dwordx4 v[74:77], v[200:201], off offset:576
	s_waitcnt vmcnt(28)
	v_pk_fma_f32 v[214:215], v[92:93], v[144:145], v[214:215]
	v_pk_fma_f32 v[212:213], v[90:91], v[142:143], v[212:213]
	global_store_dwordx4 v[186:187], v[212:215], off
	s_waitcnt vmcnt(28)
	v_pk_fma_f32 v[112:113], v[84:85], v[140:141], v[112:113]
	v_pk_fma_f32 v[110:111], v[82:83], v[138:139], v[110:111]
	global_store_dwordx4 v[186:187], v[110:113], off offset:64
	s_waitcnt vmcnt(27)
	v_pk_fma_f32 v[226:227], v[72:73], v[136:137], v[226:227]
	v_pk_fma_f32 v[224:225], v[70:71], v[134:135], v[224:225]
	global_store_dwordx4 v[186:187], v[224:227], off offset:512
	s_waitcnt vmcnt(27)
	v_pk_fma_f32 v[104:105], v[68:69], v[132:133], v[104:105]
	v_pk_fma_f32 v[102:103], v[66:67], v[130:131], v[102:103]
	global_store_dwordx4 v[186:187], v[102:105], off offset:576
	s_waitcnt vmcnt(26)
	v_pk_fma_f32 v[230:231], v[64:65], v[144:145], v[230:231]
	v_pk_fma_f32 v[228:229], v[62:63], v[142:143], v[228:229]
	global_store_dwordx4 v[190:191], v[228:231], off
	s_waitcnt vmcnt(26)
	v_pk_fma_f32 v[120:121], v[60:61], v[140:141], v[120:121]
	v_pk_fma_f32 v[118:119], v[58:59], v[138:139], v[118:119]
	global_store_dwordx4 v[190:191], v[118:121], off offset:64
	s_waitcnt vmcnt(25)
	v_pk_fma_f32 v[234:235], v[48:49], v[136:137], v[234:235]
	v_pk_fma_f32 v[232:233], v[46:47], v[134:135], v[232:233]
	global_store_dwordx4 v[190:191], v[232:235], off offset:512
	s_waitcnt vmcnt(25)
	v_pk_fma_f32 v[116:117], v[44:45], v[132:133], v[116:117]
	v_pk_fma_f32 v[114:115], v[42:43], v[130:131], v[114:115]
	global_store_dwordx4 v[190:191], v[114:117], off offset:576
	s_waitcnt vmcnt(24)
	v_pk_fma_f32 v[238:239], v[56:57], v[144:145], v[238:239]
	v_pk_fma_f32 v[236:237], v[54:55], v[142:143], v[236:237]
	global_store_dwordx4 v[194:195], v[236:239], off
	s_waitcnt vmcnt(24)
	v_pk_fma_f32 v[96:97], v[52:53], v[140:141], v[96:97]
	v_pk_fma_f32 v[94:95], v[50:51], v[138:139], v[94:95]
	global_store_dwordx4 v[194:195], v[94:97], off offset:64
	s_waitcnt vmcnt(23)
	v_pk_fma_f32 v[242:243], v[32:33], v[136:137], v[242:243]
	v_pk_fma_f32 v[240:241], v[30:31], v[134:135], v[240:241]
	global_store_dwordx4 v[194:195], v[240:243], off offset:512
	s_waitcnt vmcnt(23)
	v_pk_fma_f32 v[88:89], v[28:29], v[132:133], v[88:89]
	v_pk_fma_f32 v[86:87], v[26:27], v[130:131], v[86:87]
	global_store_dwordx4 v[194:195], v[86:89], off offset:576
	s_waitcnt vmcnt(22)
	v_pk_fma_f32 v[246:247], v[40:41], v[144:145], v[246:247]
	v_pk_fma_f32 v[244:245], v[38:39], v[142:143], v[244:245]
	global_store_dwordx4 v[198:199], v[244:247], off
	s_waitcnt vmcnt(22)
	v_pk_fma_f32 v[108:109], v[36:37], v[140:141], v[108:109]
	v_pk_fma_f32 v[106:107], v[34:35], v[138:139], v[106:107]
	global_store_dwordx4 v[198:199], v[106:109], off offset:64
	s_waitcnt vmcnt(21)
	v_pk_fma_f32 v[250:251], v[16:17], v[136:137], v[250:251]
	v_pk_fma_f32 v[248:249], v[14:15], v[134:135], v[248:249]
	global_store_dwordx4 v[198:199], v[248:251], off offset:512
	s_waitcnt vmcnt(21)
	v_pk_fma_f32 v[100:101], v[12:13], v[132:133], v[100:101]
	v_pk_fma_f32 v[98:99], v[10:11], v[130:131], v[98:99]
	global_store_dwordx4 v[198:199], v[98:101], off offset:576
	s_waitcnt vmcnt(20)
	v_pk_fma_f32 v[128:129], v[24:25], v[144:145], v[128:129]
	v_pk_fma_f32 v[126:127], v[22:23], v[142:143], v[126:127]
	global_store_dwordx4 v[202:203], v[126:129], off
	s_waitcnt vmcnt(20)
	v_pk_fma_f32 v[80:81], v[20:21], v[140:141], v[80:81]
	v_pk_fma_f32 v[78:79], v[18:19], v[138:139], v[78:79]
	global_store_dwordx4 v[202:203], v[78:81], off offset:64
	s_waitcnt vmcnt(19)
	v_pk_fma_f32 v[206:207], v[8:9], v[136:137], v[206:207]
	v_pk_fma_f32 v[204:205], v[6:7], v[134:135], v[204:205]
	global_store_dwordx4 v[202:203], v[204:207], off offset:512
	s_waitcnt vmcnt(19)
	v_pk_fma_f32 v[76:77], v[4:5], v[132:133], v[76:77]
	v_pk_fma_f32 v[74:75], v[2:3], v[130:131], v[74:75]
	global_store_dwordx4 v[202:203], v[74:77], off offset:576
	s_mov_b64 s[2:3], 0

;     __device__ __forceinline__ void operator()(const f32x4 (&acc)[2][2][4][2], const Unit& u, int wr, int wc, int fr, int fq) const {
;     ...
;         const bool isctx = u.pm >= 128;
;         const float* inb = isctx ? in_ctx : in_lat; float* outb = isctx ? out_ctx : out_lat;
;         const int pml = isctx ? u.pm - 128 : u.pm;
;         const float* gp = gate + (size_t)(isctx ? 16 : (u.pm >> 3)) * 6144;
;         const int row0 = pml * BM + wr * 64 + fr, col0 = u.pn * BM + wc * 32 + 4 * fq;
;         f32x4 gv[2][2];
; #pragma unroll
;         for (int bj = 0; bj < 2; ++bj)
; #pragma unroll
;             for (int n = 0; n < 2; ++n) gv[bj][n] = *(const f32x4*)(gp + col0 + bj * HALF + n * 16);
; #pragma unroll
;         for (int ai = 0; ai < 2; ++ai)
; #pragma unroll
;             for (int m = 0; m < 4; ++m) { const size_t ro = (size_t)(row0 + ai * HALF + m * 16) * 1024 + col0;
; #pragma unroll
;                 for (int bj = 0; bj < 2; ++bj)
; #pragma unroll
;                     for (int n = 0; n < 2; ++n) { const f32x4 x = *(const f32x4*)(inb + ro + bj * HALF + n * 16);
;                         *(f32x4*)(outb + ro + bj * HALF + n * 16) = x + gv[bj][n] * acc[ai][bj][m][n]; } }
.LBB0_1199:
	s_and_b64 s[2:3], exec, s[16:17]
	s_cselect_b32 s3, s65, s43
	s_cselect_b32 s2, s64, s42
	s_lshl_b64 s[26:27], s[26:27], 2
	s_add_u32 s26, s50, s26
	s_addc_u32 s27, s51, s27
	s_lshl_b32 s5, s18, 8
	s_add_i32 s19, s5, 0xffff8000
	s_and_b64 s[16:17], exec, s[16:17]
	s_cselect_b32 s5, s19, s5
	v_add_u32_e32 v174, s5, v160
	v_lshl_or_b32 v130, s11, 8, v161
	v_ashrrev_i32_e32 v175, 31, v174
	v_ashrrev_i32_e32 v131, 31, v130
	v_lshlrev_b64 v[146:147], 12, v[174:175]
	v_lshlrev_b64 v[172:173], 2, v[130:131]
	v_lshl_add_u64 v[146:147], s[2:3], 0, v[146:147]
	v_lshl_add_u64 v[130:131], s[26:27], 0, v[172:173]
	v_lshl_add_u64 v[170:171], v[146:147], 0, v[172:173]
	global_load_dwordx4 v[142:145], v[130:131], off
	global_load_dwordx4 v[138:141], v[130:131], off offset:64
	global_load_dwordx4 v[134:137], v[130:131], off offset:512
	s_nop 0
	global_load_dwordx4 v[130:133], v[130:131], off offset:576
	s_nop 0
	s_mov_b64 s[98:99], 0x10000
	v_lshl_add_u64 v[176:177], v[170:171], 0, s[98:99]
	s_mov_b64 s[98:99], 0x20000
	v_lshl_add_u64 v[178:179], v[170:171], 0, s[98:99]
	s_mov_b64 s[98:99], 0x30000
	v_lshl_add_u64 v[180:181], v[170:171], 0, s[98:99]
	s_mov_b64 s[98:99], 0x80000
	v_lshl_add_u64 v[182:183], v[170:171], 0, s[98:99]
	s_mov_b64 s[98:99], 0x90000
	v_lshl_add_u64 v[184:185], v[170:171], 0, s[98:99]
	s_mov_b64 s[98:99], 0xa0000
	v_lshl_add_u64 v[186:187], v[170:171], 0, s[98:99]
	s_mov_b64 s[98:99], 0xb0000
	v_lshl_add_u64 v[188:189], v[170:171], 0, s[98:99]
	global_load_dwordx4 v[204:207], v[170:171], off
	global_load_dwordx4 v[212:215], v[170:171], off offset:64
	global_load_dwordx4 v[224:227], v[170:171], off offset:512
	global_load_dwordx4 v[228:231], v[170:171], off offset:576
	global_load_dwordx4 v[232:235], v[176:177], off
	global_load_dwordx4 v[236:239], v[176:177], off offset:64
	global_load_dwordx4 v[240:243], v[176:177], off offset:512
	global_load_dwordx4 v[244:247], v[176:177], off offset:576
	global_load_dwordx4 v[248:251], v[178:179], off
	s_waitcnt vmcnt(8)
	v_pk_fma_f32 v[206:207], v[128:129], v[144:145], v[206:207]
	v_pk_fma_f32 v[204:205], v[126:127], v[142:143], v[204:205]
	global_store_dwordx4 v[170:171], v[204:207], off
	global_load_dwordx4 v[126:129], v[178:179], off offset:64
	s_waitcnt vmcnt(9)
	v_pk_fma_f32 v[214:215], v[124:125], v[140:141], v[214:215]
	v_pk_fma_f32 v[212:213], v[122:123], v[138:139], v[212:213]
	global_store_dwordx4 v[170:171], v[212:215], off offset:64
	global_load_dwordx4 v[204:207], v[178:179], off offset:512
	global_load_dwordx4 v[122:125], v[178:179], off offset:576
	s_waitcnt vmcnt(11)
	v_pk_fma_f32 v[226:227], v[112:113], v[136:137], v[226:227]
	v_pk_fma_f32 v[224:225], v[110:111], v[134:135], v[224:225]
	global_store_dwordx4 v[170:171], v[224:227], off offset:512
	global_load_dwordx4 v[212:215], v[180:181], off
	global_load_dwordx4 v[110:113], v[180:181], off offset:64
	s_waitcnt vmcnt(13)
	v_pk_fma_f32 v[230:231], v[104:105], v[132:133], v[230:231]
	v_pk_fma_f32 v[228:229], v[102:103], v[130:131], v[228:229]
	global_store_dwordx4 v[170:171], v[228:231], off offset:576
	global_load_dwordx4 v[224:227], v[180:181], off offset:512
	global_load_dwordx4 v[102:105], v[180:181], off offset:576
	s_waitcnt vmcnt(15)
	v_pk_fma_f32 v[234:235], v[120:121], v[144:145], v[234:235]
	v_pk_fma_f32 v[232:233], v[118:119], v[142:143], v[232:233]
	global_store_dwordx4 v[176:177], v[232:235], off
	global_load_dwordx4 v[228:231], v[182:183], off
	global_load_dwordx4 v[118:121], v[182:183], off offset:64
	s_waitcnt vmcnt(17)
	v_pk_fma_f32 v[238:239], v[116:117], v[140:141], v[238:239]
	v_pk_fma_f32 v[236:237], v[114:115], v[138:139], v[236:237]
	global_store_dwordx4 v[176:177], v[236:239], off offset:64
	global_load_dwordx4 v[232:235], v[182:183], off offset:512
	global_load_dwordx4 v[114:117], v[182:183], off offset:576
	s_waitcnt vmcnt(19)
	v_pk_fma_f32 v[242:243], v[96:97], v[136:137], v[242:243]
	v_pk_fma_f32 v[240:241], v[94:95], v[134:135], v[240:241]
	global_store_dwordx4 v[176:177], v[240:243], off offset:512
	global_load_dwordx4 v[236:239], v[184:185], off
	global_load_dwordx4 v[94:97], v[184:185], off offset:64
	s_waitcnt vmcnt(21)
	v_pk_fma_f32 v[246:247], v[88:89], v[132:133], v[246:247]
	v_pk_fma_f32 v[244:245], v[86:87], v[130:131], v[244:245]
	global_store_dwordx4 v[176:177], v[244:247], off offset:576
	global_load_dwordx4 v[240:243], v[184:185], off offset:512
	global_load_dwordx4 v[86:89], v[184:185], off offset:576
	s_waitcnt vmcnt(23)
	v_pk_fma_f32 v[250:251], v[108:109], v[144:145], v[250:251]
	v_pk_fma_f32 v[248:249], v[106:107], v[142:143], v[248:249]
	global_store_dwordx4 v[178:179], v[248:251], off
	global_load_dwordx4 v[244:247], v[186:187], off
	global_load_dwordx4 v[106:109], v[186:187], off offset:64
	s_waitcnt vmcnt(24)
;     __device__ __forceinline__ void operator()(const f32x4 (&acc)[2][2][4][2], const Unit& u, int wr, int wc, int fr, int fq) const {
;     ...
;         for (int ai = 0; ai < 2; ++ai)
; #pragma unroll
;             for (int m = 0; m < 4; ++m) { const size_t ro = (size_t)(row0 + ai * HALF + m * 16) * 1024 + col0;
; #pragma unroll
;                 for (int bj = 0; bj < 2; ++bj)
; #pragma unroll
;                     for (int n = 0; n < 2; ++n) { const f32x4 x = *(const f32x4*)(inb + ro + bj * HALF + n * 16);
;                         *(f32x4*)(outb + ro + bj * HALF + n * 16) = x + gv[bj][n] * acc[ai][bj][m][n]; } }
	v_pk_fma_f32 v[128:129], v[100:101], v[140:141], v[128:129]
	v_pk_fma_f32 v[126:127], v[98:99], v[138:139], v[126:127]
	global_store_dwordx4 v[178:179], v[126:129], off offset:64
	global_load_dwordx4 v[248:251], v[186:187], off offset:512
	global_load_dwordx4 v[98:101], v[186:187], off offset:576
	s_waitcnt vmcnt(25)
	v_pk_fma_f32 v[206:207], v[80:81], v[136:137], v[206:207]
	v_pk_fma_f32 v[204:205], v[78:79], v[134:135], v[204:205]
	global_store_dwordx4 v[178:179], v[204:207], off offset:512
	global_load_dwordx4 v[126:129], v[188:189], off
	global_load_dwordx4 v[78:81], v[188:189], off offset:64
	s_waitcnt vmcnt(27)
	v_pk_fma_f32 v[124:125], v[76:77], v[132:133], v[124:125]
	v_pk_fma_f32 v[122:123], v[74:75], v[130:131], v[122:123]
	global_store_dwordx4 v[178:179], v[122:125], off offset:576
	global_load_dwordx4 v[204:207], v[188:189], off offset:512
	global_load_dwordx4 v[74:77], v[188:189], off offset:576
	s_waitcnt vmcnt(28)
	v_pk_fma_f32 v[214:215], v[92:93], v[144:145], v[214:215]
	v_pk_fma_f32 v[212:213], v[90:91], v[142:143], v[212:213]
	global_store_dwordx4 v[180:181], v[212:215], off
	s_waitcnt vmcnt(28)
	v_pk_fma_f32 v[112:113], v[84:85], v[140:141], v[112:113]
	v_pk_fma_f32 v[110:111], v[82:83], v[138:139], v[110:111]
	global_store_dwordx4 v[180:181], v[110:113], off offset:64
	s_waitcnt vmcnt(27)
	v_pk_fma_f32 v[226:227], v[72:73], v[136:137], v[226:227]
	v_pk_fma_f32 v[224:225], v[70:71], v[134:135], v[224:225]
	global_store_dwordx4 v[180:181], v[224:227], off offset:512
	s_waitcnt vmcnt(27)
	v_pk_fma_f32 v[104:105], v[68:69], v[132:133], v[104:105]
	v_pk_fma_f32 v[102:103], v[66:67], v[130:131], v[102:103]
	global_store_dwordx4 v[180:181], v[102:105], off offset:576
	s_waitcnt vmcnt(26)
	v_pk_fma_f32 v[230:231], v[64:65], v[144:145], v[230:231]
	v_pk_fma_f32 v[228:229], v[62:63], v[142:143], v[228:229]
	global_store_dwordx4 v[182:183], v[228:231], off
	s_waitcnt vmcnt(26)
	v_pk_fma_f32 v[120:121], v[60:61], v[140:141], v[120:121]
	v_pk_fma_f32 v[118:119], v[58:59], v[138:139], v[118:119]
	global_store_dwordx4 v[182:183], v[118:121], off offset:64
	s_waitcnt vmcnt(25)
	v_pk_fma_f32 v[234:235], v[48:49], v[136:137], v[234:235]
	v_pk_fma_f32 v[232:233], v[46:47], v[134:135], v[232:233]
	global_store_dwordx4 v[182:183], v[232:235], off offset:512
	s_waitcnt vmcnt(25)
	v_pk_fma_f32 v[116:117], v[44:45], v[132:133], v[116:117]
	v_pk_fma_f32 v[114:115], v[42:43], v[130:131], v[114:115]
	global_store_dwordx4 v[182:183], v[114:117], off offset:576
	s_waitcnt vmcnt(24)
	v_pk_fma_f32 v[238:239], v[56:57], v[144:145], v[238:239]
	v_pk_fma_f32 v[236:237], v[54:55], v[142:143], v[236:237]
	global_store_dwordx4 v[184:185], v[236:239], off
	s_waitcnt vmcnt(24)
	v_pk_fma_f32 v[96:97], v[52:53], v[140:141], v[96:97]
	v_pk_fma_f32 v[94:95], v[50:51], v[138:139], v[94:95]
	global_store_dwordx4 v[184:185], v[94:97], off offset:64
	s_waitcnt vmcnt(23)
	v_pk_fma_f32 v[242:243], v[32:33], v[136:137], v[242:243]
	v_pk_fma_f32 v[240:241], v[30:31], v[134:135], v[240:241]
	global_store_dwordx4 v[184:185], v[240:243], off offset:512
	s_waitcnt vmcnt(23)
	v_pk_fma_f32 v[88:89], v[28:29], v[132:133], v[88:89]
	v_pk_fma_f32 v[86:87], v[26:27], v[130:131], v[86:87]
	global_store_dwordx4 v[184:185], v[86:89], off offset:576
	s_waitcnt vmcnt(22)
	v_pk_fma_f32 v[246:247], v[40:41], v[144:145], v[246:247]
	v_pk_fma_f32 v[244:245], v[38:39], v[142:143], v[244:245]
	global_store_dwordx4 v[186:187], v[244:247], off
	s_waitcnt vmcnt(22)
	v_pk_fma_f32 v[108:109], v[36:37], v[140:141], v[108:109]
	v_pk_fma_f32 v[106:107], v[34:35], v[138:139], v[106:107]
	global_store_dwordx4 v[186:187], v[106:109], off offset:64
	s_waitcnt vmcnt(21)
	v_pk_fma_f32 v[250:251], v[16:17], v[136:137], v[250:251]
	v_pk_fma_f32 v[248:249], v[14:15], v[134:135], v[248:249]
	global_store_dwordx4 v[186:187], v[248:251], off offset:512
	s_waitcnt vmcnt(21)
	v_pk_fma_f32 v[100:101], v[12:13], v[132:133], v[100:101]
	v_pk_fma_f32 v[98:99], v[10:11], v[130:131], v[98:99]
	global_store_dwordx4 v[186:187], v[98:101], off offset:576
	s_waitcnt vmcnt(20)
	v_pk_fma_f32 v[128:129], v[24:25], v[144:145], v[128:129]
	v_pk_fma_f32 v[126:127], v[22:23], v[142:143], v[126:127]
	global_store_dwordx4 v[188:189], v[126:129], off
	s_waitcnt vmcnt(20)
	v_pk_fma_f32 v[80:81], v[20:21], v[140:141], v[80:81]
	v_pk_fma_f32 v[78:79], v[18:19], v[138:139], v[78:79]
	global_store_dwordx4 v[188:189], v[78:81], off offset:64
	s_waitcnt vmcnt(19)
	v_pk_fma_f32 v[206:207], v[8:9], v[136:137], v[206:207]
	v_pk_fma_f32 v[204:205], v[6:7], v[134:135], v[204:205]
	global_store_dwordx4 v[188:189], v[204:207], off offset:512
	s_waitcnt vmcnt(19)
	v_pk_fma_f32 v[76:77], v[4:5], v[132:133], v[76:77]
	v_pk_fma_f32 v[74:75], v[2:3], v[130:131], v[74:75]
	global_store_dwordx4 v[188:189], v[74:77], off offset:576
	s_mov_b64 s[2:3], 0
